# K-loop compute segments: only MFMAs between the two barriers (setprio moved outside, mid flips and satisfied lgkmcnt wait dropped)
# baseline (speedup 1.0000x reference)
; #define PG8_STAGE(bufoff, gbase, voff, h64) do { \
;         __builtin_amdgcn_global_load_lds((const unsigned*)((const char*)(gbase) + (voff)), (LAS unsigned*)(lds + (bufoff) + ldsw), 16, 0, 0); \
;         __builtin_amdgcn_global_load_lds((const unsigned*)((const char*)(gbase) + (h64) + (voff)), (LAS unsigned*)(lds + (bufoff) + ldsw + 8192), 16, 0, 0); } while (0)
; #define PG8_LDA(dst, b, h) do { _Pragma("unroll") for (int m = 0; m < 4; ++m) { dst[m].lo = *(const LAS f16x8*)(lds + PG8_SA(b, h) + aoff + m * 2048); dst[m].hi = *(const LAS f16x8*)(lds + PG8_SA(b, h) + aoff + m * 2048 + 1024); } } while (0)
; #define PG8_LDB(dst, b, h) do { _Pragma("unroll") for (int n = 0; n < 2; ++n) { dst[n].lo = *(const LAS f16x8*)(lds + PG8_SB(b, h) + boff + n * 2048); dst[n].hi = *(const LAS f16x8*)(lds + PG8_SB(b, h) + boff + n * 2048 + 1024); } } while (0)
; #define PG8_WAIT_V(n) asm volatile("s_waitcnt vmcnt(" #n ")" ::: "memory")
; #define PG8_WAIT_L(n) asm volatile("s_waitcnt lgkmcnt(" #n ")" ::: "memory")
; #define PG8_BAR __builtin_amdgcn_s_barrier()
; #define PG8_SCHED __builtin_amdgcn_sched_barrier(0)
; template <bool F8 = false, class Sched, class Epi>
; __device__ __forceinline__ void gemm_phase(LAS unsigned char* lds, const Sched& S, const Epi& E) {
;     ...
;             PG8_LDB(B0, 0, 0); PG8_LDB(B1, 0, 1); PG8_SCHED; PG8_LDA(At, 0, 0); PG8_STAGE(PG8_SA(1, 1), a1 + chs, cvA, ch64);
;             PG8_WAIT_V(8); PG8_WAIT_L(0); PG8_BAR; PG8_MMA(0, 0, At, B0); PG8_MMA(0, 1, At, B1); PG8_BAR; PG8_SCHED;
;             PG8_LDA(At, 0, 1); PG8_STAGE(PG8_SB(0, 0), b2, vB2, h2); PG8_STAGE(PG8_SB(0, 1), b2 + bhs2, vB2, h2); PG8_STAGE(PG8_SA(0, 0), a2, vA2, h2);
;             PG8_WAIT_V(8); PG8_WAIT_L(0); PG8_BAR; PG8_MMA(1, 0, At, B0); PG8_MMA(1, 1, At, B1); PG8_BAR; PG8_SCHED;
.LBB0_73:
	s_add_u32 s24, s12, s8
	s_addc_u32 s25, s13, s9
	s_add_u32 s26, s24, 0x100
	s_addc_u32 s27, s25, 0
	s_add_u32 s36, s71, s8
	s_addc_u32 s68, s72, s9
	s_cmpk_eq_i32 s8, 0x300
	s_cselect_b64 vcc, -1, 0
	s_and_b64 s[24:25], vcc, exec
	s_cselect_b32 s25, s73, s27
	s_cselect_b32 s24, s74, s26
	s_cselect_b32 s27, s75, s68
	s_cselect_b32 s26, s80, s36
	s_add_i32 s36, 0, 0x10000
	s_add_i32 s68, 0, 0x14000
	v_add_u32_e32 v0, s36, v163
	v_add_u32_e32 v12, s68, v163
	ds_read_b128 v[16:19], v0
	ds_read_b128 v[20:23], v0 offset:1024
	ds_read_b128 v[24:27], v0 offset:2048
	ds_read_b128 v[28:31], v0 offset:3072
	ds_read_b128 v[0:3], v12
	ds_read_b128 v[4:7], v12 offset:1024
	ds_read_b128 v[8:11], v12 offset:2048
	ds_read_b128 v[12:15], v12 offset:3072
	v_cndmask_b32_e32 v32, v164, v166, vcc
	v_cndmask_b32_e32 v172, v162, v175, vcc
	v_lshl_add_u64 v[170:171], v[168:169], 0, s[8:9]
	v_lshl_add_u64 v[192:193], v[170:171], 0, s[58:59]
	s_add_i32 m0, s31, 0xc000
	ds_read_b128 v[176:179], v174
	ds_read_b128 v[180:183], v174 offset:1024
	ds_read_b128 v[184:187], v174 offset:2048
	ds_read_b128 v[188:191], v174 offset:3072
	ds_read_b128 v[198:201], v174 offset:4096
	ds_read_b128 v[202:205], v174 offset:5120
	ds_read_b128 v[206:209], v174 offset:6144
	ds_read_b128 v[210:213], v174 offset:7168
	global_load_lds_dwordx4 v[192:193], off
	v_lshl_add_u64 v[170:171], v[170:171], 0, s[76:77]
	s_add_i32 m0, s31, 0xe000
	s_nop 0
	global_load_lds_dwordx4 v[170:171], off
	s_waitcnt vmcnt(8)
	s_waitcnt lgkmcnt(0)
	s_setprio 1
	s_barrier
	v_mfma_scale_f32_16x16x128_f8f6f4 v[158:161], v[16:23], v[176:183], v[158:161], v220, v221 op_sel_hi:[0,0,0]
	v_mfma_scale_f32_16x16x128_f8f6f4 v[154:157], v[24:31], v[176:183], v[154:157], v220, v221 op_sel_hi:[0,0,0]
	v_mfma_scale_f32_16x16x128_f8f6f4 v[150:153], v[16:23], v[184:191], v[150:153], v220, v221 op_sel_hi:[0,0,0]
	v_mfma_scale_f32_16x16x128_f8f6f4 v[146:149], v[24:31], v[184:191], v[146:149], v220, v221 op_sel_hi:[0,0,0]
	v_mfma_scale_f32_16x16x128_f8f6f4 v[142:145], v[16:23], v[198:205], v[142:145], v220, v221 op_sel_hi:[0,0,0]
	v_mfma_scale_f32_16x16x128_f8f6f4 v[138:141], v[24:31], v[198:205], v[138:141], v220, v221 op_sel_hi:[0,0,0]
	v_mfma_scale_f32_16x16x128_f8f6f4 v[134:137], v[16:23], v[206:213], v[134:137], v220, v221 op_sel_hi:[0,0,0]
	v_mfma_scale_f32_16x16x128_f8f6f4 v[130:133], v[24:31], v[206:213], v[130:133], v220, v221 op_sel_hi:[0,0,0]
	v_mfma_scale_f32_16x16x128_f8f6f4 v[126:129], v[0:7], v[176:183], v[126:129], v220, v221 op_sel_hi:[0,0,0]
	v_mfma_scale_f32_16x16x128_f8f6f4 v[122:125], v[8:15], v[176:183], v[122:125], v220, v221 op_sel_hi:[0,0,0]
	v_mfma_scale_f32_16x16x128_f8f6f4 v[118:121], v[0:7], v[184:191], v[118:121], v220, v221 op_sel_hi:[0,0,0]
	v_mfma_scale_f32_16x16x128_f8f6f4 v[114:117], v[8:15], v[184:191], v[114:117], v220, v221 op_sel_hi:[0,0,0]
	v_mfma_scale_f32_16x16x128_f8f6f4 v[110:113], v[0:7], v[198:205], v[110:113], v220, v221 op_sel_hi:[0,0,0]
	v_mfma_scale_f32_16x16x128_f8f6f4 v[106:109], v[8:15], v[198:205], v[106:109], v220, v221 op_sel_hi:[0,0,0]
	v_mfma_scale_f32_16x16x128_f8f6f4 v[102:105], v[0:7], v[206:213], v[102:105], v220, v221 op_sel_hi:[0,0,0]
	v_mfma_scale_f32_16x16x128_f8f6f4 v[98:101], v[8:15], v[206:213], v[98:101], v220, v221 op_sel_hi:[0,0,0]
	s_barrier
	s_setprio 0
	v_mov_b32_e32 v173, v33
	s_add_i32 s36, s36, s49
	v_lshl_add_u64 v[170:171], s[26:27], 0, v[172:173]
	s_mov_b32 m0, s36
	ds_read_b128 v[176:179], v174 offset:16384
	ds_read_b128 v[180:183], v174 offset:17408
	ds_read_b128 v[184:187], v174 offset:18432
	ds_read_b128 v[188:191], v174 offset:19456
	ds_read_b128 v[198:201], v174 offset:20480
	ds_read_b128 v[202:205], v174 offset:21504
	ds_read_b128 v[206:209], v174 offset:22528
	ds_read_b128 v[210:213], v174 offset:23552
	global_load_lds_dwordx4 v172, s[26:27]
	v_lshl_add_u64 v[172:173], v[170:171], 0, s[38:39]
	s_add_i32 m0, s36, 0x2000
	s_add_i32 s26, s68, s49
	global_load_lds_dwordx4 v[172:173], off
	v_lshl_add_u64 v[172:173], v[170:171], 0, s[60:61]
	s_mov_b32 m0, s26
	s_nop 0
	global_load_lds_dwordx4 v[172:173], off
	v_lshl_add_u64 v[172:173], v[170:171], 0, s[0:1]
	s_add_i32 m0, s26, 0x2000
	s_nop 0
	global_load_lds_dwordx4 v[172:173], off
	v_lshl_add_u64 v[172:173], s[24:25], 0, v[32:33]
	s_mov_b32 m0, s31
	v_lshl_add_u64 v[192:193], v[172:173], 0, s[38:39]
	global_load_lds_dwordx4 v[172:173], off
	s_mov_b32 m0, s34
	s_nop 0
	global_load_lds_dwordx4 v[192:193], off
	s_waitcnt vmcnt(8)
	s_waitcnt lgkmcnt(0)
	s_setprio 1
	s_barrier
	v_mfma_scale_f32_16x16x128_f8f6f4 v[94:97], v[16:23], v[176:183], v[94:97], v220, v221 op_sel_hi:[0,0,0]
	v_mfma_scale_f32_16x16x128_f8f6f4 v[90:93], v[24:31], v[176:183], v[90:93], v220, v221 op_sel_hi:[0,0,0]
	v_mfma_scale_f32_16x16x128_f8f6f4 v[86:89], v[16:23], v[184:191], v[86:89], v220, v221 op_sel_hi:[0,0,0]
	v_mfma_scale_f32_16x16x128_f8f6f4 v[82:85], v[24:31], v[184:191], v[82:85], v220, v221 op_sel_hi:[0,0,0]
	v_mfma_scale_f32_16x16x128_f8f6f4 v[78:81], v[16:23], v[198:205], v[78:81], v220, v221 op_sel_hi:[0,0,0]
	v_mfma_scale_f32_16x16x128_f8f6f4 v[74:77], v[24:31], v[198:205], v[74:77], v220, v221 op_sel_hi:[0,0,0]
	v_mfma_scale_f32_16x16x128_f8f6f4 v[70:73], v[16:23], v[206:213], v[70:73], v220, v221 op_sel_hi:[0,0,0]
	v_mfma_scale_f32_16x16x128_f8f6f4 v[66:69], v[24:31], v[206:213], v[66:69], v220, v221 op_sel_hi:[0,0,0]
	v_mfma_scale_f32_16x16x128_f8f6f4 v[62:65], v[0:7], v[176:183], v[62:65], v220, v221 op_sel_hi:[0,0,0]
	v_mfma_scale_f32_16x16x128_f8f6f4 v[58:61], v[8:15], v[176:183], v[58:61], v220, v221 op_sel_hi:[0,0,0]
	v_mfma_scale_f32_16x16x128_f8f6f4 v[54:57], v[0:7], v[184:191], v[54:57], v220, v221 op_sel_hi:[0,0,0]
	v_mfma_scale_f32_16x16x128_f8f6f4 v[50:53], v[8:15], v[184:191], v[50:53], v220, v221 op_sel_hi:[0,0,0]
	v_mfma_scale_f32_16x16x128_f8f6f4 v[46:49], v[0:7], v[198:205], v[46:49], v220, v221 op_sel_hi:[0,0,0]
	v_mfma_scale_f32_16x16x128_f8f6f4 v[42:45], v[8:15], v[198:205], v[42:45], v220, v221 op_sel_hi:[0,0,0]
	v_mfma_scale_f32_16x16x128_f8f6f4 v[38:41], v[0:7], v[206:213], v[38:41], v220, v221 op_sel_hi:[0,0,0]
	v_mfma_scale_f32_16x16x128_f8f6f4 v[34:37], v[8:15], v[206:213], v[34:37], v220, v221 op_sel_hi:[0,0,0]
	s_barrier
; #define PG8_STAGE(bufoff, gbase, voff, h64) do { \
;         __builtin_amdgcn_global_load_lds((const unsigned*)((const char*)(gbase) + (voff)), (LAS unsigned*)(lds + (bufoff) + ldsw), 16, 0, 0); \
;         __builtin_amdgcn_global_load_lds((const unsigned*)((const char*)(gbase) + (h64) + (voff)), (LAS unsigned*)(lds + (bufoff) + ldsw + 8192), 16, 0, 0); } while (0)
; #define PG8_LDA(dst, b, h) do { _Pragma("unroll") for (int m = 0; m < 4; ++m) { dst[m].lo = *(const LAS f16x8*)(lds + PG8_SA(b, h) + aoff + m * 2048); dst[m].hi = *(const LAS f16x8*)(lds + PG8_SA(b, h) + aoff + m * 2048 + 1024); } } while (0)
; #define PG8_LDB(dst, b, h) do { _Pragma("unroll") for (int n = 0; n < 2; ++n) { dst[n].lo = *(const LAS f16x8*)(lds + PG8_SB(b, h) + boff + n * 2048); dst[n].hi = *(const LAS f16x8*)(lds + PG8_SB(b, h) + boff + n * 2048 + 1024); } } while (0)
; #define PG8_WAIT_V(n) asm volatile("s_waitcnt vmcnt(" #n ")" ::: "memory")
; #define PG8_WAIT_L(n) asm volatile("s_waitcnt lgkmcnt(" #n ")" ::: "memory")
; #define PG8_BAR __builtin_amdgcn_s_barrier()
; #define PG8_SCHED __builtin_amdgcn_sched_barrier(0)
; template <bool F8 = false, class Sched, class Epi>
; __device__ __forceinline__ void gemm_phase(LAS unsigned char* lds, const Sched& S, const Epi& E) {
;     ...
;             PG8_LDB(B0, 1, 0); PG8_LDB(B1, 1, 1); PG8_SCHED; PG8_LDA(At, 1, 0); PG8_STAGE(PG8_SA(0, 1), a2 + hs2, vA2, h2);
;             PG8_WAIT_V(8); PG8_WAIT_L(0); PG8_BAR; PG8_MMA(0, 0, At, B0); PG8_MMA(0, 1, At, B1); PG8_BAR; PG8_SCHED;
;             PG8_LDA(At, 1, 1); PG8_STAGE(PG8_SB(1, 0), b3, vB2, h2); PG8_STAGE(PG8_SB(1, 1), b3 + bhs2, vB2, h2); PG8_STAGE(PG8_SA(1, 0), a3, vA2, h2);
;             PG8_WAIT_V(8); PG8_WAIT_L(0); PG8_BAR; PG8_MMA(1, 0, At, B0); PG8_MMA(1, 1, At, B1); PG8_BAR; PG8_SCHED;
;         }
;         if (wr == 0) PG8_BAR;
	s_setprio 0
	s_add_i32 s24, 0, 0x18000
	s_add_i32 s25, 0, 0x1c000
	v_add_u32_e32 v12, s24, v163
	v_add_u32_e32 v28, s25, v163
	ds_read_b128 v[0:3], v12
	ds_read_b128 v[4:7], v12 offset:1024
	ds_read_b128 v[8:11], v12 offset:2048
	ds_read_b128 v[12:15], v12 offset:3072
	ds_read_b128 v[16:19], v28
	ds_read_b128 v[20:23], v28 offset:1024
	ds_read_b128 v[24:27], v28 offset:2048
	ds_read_b128 v[28:31], v28 offset:3072
	s_mov_b32 m0, s35
	v_lshl_add_u64 v[192:193], v[172:173], 0, s[60:61]
	ds_read_b128 v[176:179], v174 offset:32768
	ds_read_b128 v[180:183], v174 offset:33792
	ds_read_b128 v[184:187], v174 offset:34816
	ds_read_b128 v[188:191], v174 offset:35840
	ds_read_b128 v[198:201], v174 offset:36864
	ds_read_b128 v[202:205], v174 offset:37888
	ds_read_b128 v[206:209], v174 offset:38912
	ds_read_b128 v[210:213], v174 offset:39936
	global_load_lds_dwordx4 v[192:193], off
	v_lshl_add_u64 v[192:193], v[172:173], 0, s[0:1]
	s_mov_b32 m0, s37
	s_nop 0
	global_load_lds_dwordx4 v[192:193], off
	s_waitcnt vmcnt(8)
	s_waitcnt lgkmcnt(0)
	s_setprio 1
	s_barrier
	v_mfma_scale_f32_16x16x128_f8f6f4 v[158:161], v[0:7], v[176:183], v[158:161], v220, v221 op_sel_hi:[0,0,0]
	v_mfma_scale_f32_16x16x128_f8f6f4 v[154:157], v[8:15], v[176:183], v[154:157], v220, v221 op_sel_hi:[0,0,0]
	v_mfma_scale_f32_16x16x128_f8f6f4 v[150:153], v[0:7], v[184:191], v[150:153], v220, v221 op_sel_hi:[0,0,0]
	v_mfma_scale_f32_16x16x128_f8f6f4 v[146:149], v[8:15], v[184:191], v[146:149], v220, v221 op_sel_hi:[0,0,0]
	v_mfma_scale_f32_16x16x128_f8f6f4 v[142:145], v[0:7], v[198:205], v[142:145], v220, v221 op_sel_hi:[0,0,0]
	v_mfma_scale_f32_16x16x128_f8f6f4 v[138:141], v[8:15], v[198:205], v[138:141], v220, v221 op_sel_hi:[0,0,0]
	v_mfma_scale_f32_16x16x128_f8f6f4 v[134:137], v[0:7], v[206:213], v[134:137], v220, v221 op_sel_hi:[0,0,0]
	v_mfma_scale_f32_16x16x128_f8f6f4 v[130:133], v[8:15], v[206:213], v[130:133], v220, v221 op_sel_hi:[0,0,0]
	v_mfma_scale_f32_16x16x128_f8f6f4 v[126:129], v[16:23], v[176:183], v[126:129], v220, v221 op_sel_hi:[0,0,0]
	v_mfma_scale_f32_16x16x128_f8f6f4 v[122:125], v[24:31], v[176:183], v[122:125], v220, v221 op_sel_hi:[0,0,0]
	v_mfma_scale_f32_16x16x128_f8f6f4 v[118:121], v[16:23], v[184:191], v[118:121], v220, v221 op_sel_hi:[0,0,0]
	v_mfma_scale_f32_16x16x128_f8f6f4 v[114:117], v[24:31], v[184:191], v[114:117], v220, v221 op_sel_hi:[0,0,0]
	v_mfma_scale_f32_16x16x128_f8f6f4 v[110:113], v[16:23], v[198:205], v[110:113], v220, v221 op_sel_hi:[0,0,0]
	v_mfma_scale_f32_16x16x128_f8f6f4 v[106:109], v[24:31], v[198:205], v[106:109], v220, v221 op_sel_hi:[0,0,0]
	v_mfma_scale_f32_16x16x128_f8f6f4 v[102:105], v[16:23], v[206:213], v[102:105], v220, v221 op_sel_hi:[0,0,0]
	v_mfma_scale_f32_16x16x128_f8f6f4 v[98:101], v[24:31], v[206:213], v[98:101], v220, v221 op_sel_hi:[0,0,0]
	s_barrier
	s_setprio 0
	s_add_i32 s24, s24, s49
	v_lshl_add_u64 v[192:193], v[170:171], 0, s[40:41]
	s_mov_b32 m0, s24
	ds_read_b128 v[176:179], v174 offset:49152
	ds_read_b128 v[180:183], v174 offset:50176
	ds_read_b128 v[184:187], v174 offset:51200
	ds_read_b128 v[188:191], v174 offset:52224
	ds_read_b128 v[198:201], v174 offset:53248
	ds_read_b128 v[202:205], v174 offset:54272
	ds_read_b128 v[206:209], v174 offset:55296
	ds_read_b128 v[210:213], v174 offset:56320
	global_load_lds_dwordx4 v[192:193], off
	v_lshl_add_u64 v[192:193], v[170:171], 0, s[56:57]
	s_add_i32 m0, s24, 0x2000
	s_add_i32 s24, s25, s49
	global_load_lds_dwordx4 v[192:193], off
	v_lshl_add_u64 v[192:193], v[170:171], 0, s[58:59]
	s_mov_b32 m0, s24
	v_lshl_add_u64 v[170:171], v[170:171], 0, s[76:77]
	global_load_lds_dwordx4 v[192:193], off
	s_add_i32 m0, s24, 0x2000
	s_nop 0
	global_load_lds_dwordx4 v[170:171], off
	v_lshl_add_u64 v[170:171], v[172:173], 0, s[40:41]
	s_mov_b32 m0, s42
	s_nop 0
	global_load_lds_dwordx4 v[170:171], off
	v_lshl_add_u64 v[170:171], v[172:173], 0, s[56:57]
	s_mov_b32 m0, s43
	s_nop 0
	global_load_lds_dwordx4 v[170:171], off
	s_waitcnt vmcnt(8)
	s_waitcnt lgkmcnt(0)
	s_setprio 1
	s_barrier
	v_mfma_scale_f32_16x16x128_f8f6f4 v[94:97], v[0:7], v[176:183], v[94:97], v220, v221 op_sel_hi:[0,0,0]
	v_mfma_scale_f32_16x16x128_f8f6f4 v[90:93], v[8:15], v[176:183], v[90:93], v220, v221 op_sel_hi:[0,0,0]
	v_mfma_scale_f32_16x16x128_f8f6f4 v[86:89], v[0:7], v[184:191], v[86:89], v220, v221 op_sel_hi:[0,0,0]
	v_mfma_scale_f32_16x16x128_f8f6f4 v[82:85], v[8:15], v[184:191], v[82:85], v220, v221 op_sel_hi:[0,0,0]
	v_mfma_scale_f32_16x16x128_f8f6f4 v[78:81], v[0:7], v[198:205], v[78:81], v220, v221 op_sel_hi:[0,0,0]
	v_mfma_scale_f32_16x16x128_f8f6f4 v[74:77], v[8:15], v[198:205], v[74:77], v220, v221 op_sel_hi:[0,0,0]
	v_mfma_scale_f32_16x16x128_f8f6f4 v[70:73], v[0:7], v[206:213], v[70:73], v220, v221 op_sel_hi:[0,0,0]
	v_mfma_scale_f32_16x16x128_f8f6f4 v[66:69], v[8:15], v[206:213], v[66:69], v220, v221 op_sel_hi:[0,0,0]
	v_mfma_scale_f32_16x16x128_f8f6f4 v[62:65], v[16:23], v[176:183], v[62:65], v220, v221 op_sel_hi:[0,0,0]
	v_mfma_scale_f32_16x16x128_f8f6f4 v[58:61], v[24:31], v[176:183], v[58:61], v220, v221 op_sel_hi:[0,0,0]
	v_mfma_scale_f32_16x16x128_f8f6f4 v[54:57], v[16:23], v[184:191], v[54:57], v220, v221 op_sel_hi:[0,0,0]
	v_mfma_scale_f32_16x16x128_f8f6f4 v[50:53], v[24:31], v[184:191], v[50:53], v220, v221 op_sel_hi:[0,0,0]
	v_mfma_scale_f32_16x16x128_f8f6f4 v[46:49], v[16:23], v[198:205], v[46:49], v220, v221 op_sel_hi:[0,0,0]
	v_mfma_scale_f32_16x16x128_f8f6f4 v[42:45], v[24:31], v[198:205], v[42:45], v220, v221 op_sel_hi:[0,0,0]
	v_mfma_scale_f32_16x16x128_f8f6f4 v[38:41], v[16:23], v[206:213], v[38:41], v220, v221 op_sel_hi:[0,0,0]
	v_mfma_scale_f32_16x16x128_f8f6f4 v[34:37], v[24:31], v[206:213], v[34:37], v220, v221 op_sel_hi:[0,0,0]
	s_barrier
	s_setprio 0
	s_add_i32 s81, s81, 2
	s_add_u32 s8, s8, 0x100
	s_addc_u32 s9, s9, 0
	s_cmp_gt_u32 s81, 5
	s_cbranch_scc0 .LBB0_73
	v_readlane_b32 s8, v251, 12
	v_readlane_b32 s9, v251, 13
	s_and_b64 vcc, exec, s[8:9]
	s_cbranch_vccz .LBB0_76
	s_barrier

; #define PG8_STAGE(bufoff, gbase, voff, h64) do { \
;         __builtin_amdgcn_global_load_lds((const unsigned*)((const char*)(gbase) + (voff)), (LAS unsigned*)(lds + (bufoff) + ldsw), 16, 0, 0); \
;         __builtin_amdgcn_global_load_lds((const unsigned*)((const char*)(gbase) + (h64) + (voff)), (LAS unsigned*)(lds + (bufoff) + ldsw + 8192), 16, 0, 0); } while (0)
; #define PG8_LDA(dst, b, h) do { _Pragma("unroll") for (int m = 0; m < 4; ++m) { dst[m].lo = *(const LAS f16x8*)(lds + PG8_SA(b, h) + aoff + m * 2048); dst[m].hi = *(const LAS f16x8*)(lds + PG8_SA(b, h) + aoff + m * 2048 + 1024); } } while (0)
; #define PG8_LDB(dst, b, h) do { _Pragma("unroll") for (int n = 0; n < 2; ++n) { dst[n].lo = *(const LAS f16x8*)(lds + PG8_SB(b, h) + boff + n * 2048); dst[n].hi = *(const LAS f16x8*)(lds + PG8_SB(b, h) + boff + n * 2048 + 1024); } } while (0)
; #define PG8_WAIT_V(n) asm volatile("s_waitcnt vmcnt(" #n ")" ::: "memory")
; #define PG8_WAIT_L(n) asm volatile("s_waitcnt lgkmcnt(" #n ")" ::: "memory")
; #define PG8_BAR __builtin_amdgcn_s_barrier()
; #define PG8_SCHED __builtin_amdgcn_sched_barrier(0)
; template <bool F8 = false, class Sched, class Epi>
; __device__ __forceinline__ void gemm_phase(LAS unsigned char* lds, const Sched& S, const Epi& E) {
;     ...
;             PG8_LDB(B0, 0, 0); PG8_LDB(B1, 0, 1); PG8_SCHED; PG8_LDA(At, 0, 0); PG8_STAGE(PG8_SA(1, 1), a1 + chs, cvA, ch64);
;             PG8_WAIT_V(8); PG8_WAIT_L(0); PG8_BAR; PG8_MMA(0, 0, At, B0); PG8_MMA(0, 1, At, B1); PG8_BAR; PG8_SCHED;
;             PG8_LDA(At, 0, 1); PG8_STAGE(PG8_SB(0, 0), b2, vB2, h2); PG8_STAGE(PG8_SB(0, 1), b2 + bhs2, vB2, h2); PG8_STAGE(PG8_SA(0, 0), a2, vA2, h2);
;             PG8_WAIT_V(8); PG8_WAIT_L(0); PG8_BAR; PG8_MMA(1, 0, At, B0); PG8_MMA(1, 1, At, B1); PG8_BAR; PG8_SCHED;
.LBB0_214:
	s_add_i32 s79, s79, 2
	s_add_u32 vcc_lo, s14, s10
	s_addc_u32 vcc_hi, s15, s11
	s_add_u32 vcc_lo, vcc_lo, 0x100
	s_addc_u32 vcc_hi, vcc_hi, 0
	s_and_b64 s[86:87], exec, s[86:87]
	s_cselect_b32 vcc_hi, s29, vcc_hi
	s_cselect_b32 vcc_lo, s96, vcc_lo
	s_add_i32 s86, 0, 0x10000
	s_add_i32 s45, 0, 0x14000
	v_add_u32_e32 v150, s86, v187
	v_add_u32_e32 v166, s45, v187
	ds_read_b128 v[138:141], v150
	ds_read_b128 v[142:145], v150 offset:1024
	ds_read_b128 v[146:149], v150 offset:2048
	ds_read_b128 v[150:153], v150 offset:3072
	ds_read_b128 v[154:157], v166
	ds_read_b128 v[158:161], v166 offset:1024
	ds_read_b128 v[162:165], v166 offset:2048
	ds_read_b128 v[166:169], v166 offset:3072
	v_lshl_add_u64 v[182:183], v[132:133], 0, s[10:11]
	s_add_i32 m0, s71, 0xc000
	ds_read_b128 v[170:173], v202
	ds_read_b128 v[174:177], v202 offset:1024
	ds_read_b128 v[178:181], v202 offset:2048
	ds_read_b128 v[190:193], v202 offset:3072
	ds_read_b128 v[198:201], v202 offset:4096
	ds_read_b128 v[204:207], v202 offset:5120
	ds_read_b128 v[208:211], v202 offset:6144
	ds_read_b128 v[212:215], v202 offset:7168
	global_load_lds_dwordx4 v[182:183], off
	v_lshl_add_u64 v[182:183], v[134:135], 0, s[10:11]
	s_add_i32 m0, s71, 0xe000
	s_nop 0
	global_load_lds_dwordx4 v[182:183], off
	s_waitcnt vmcnt(8)
	s_waitcnt lgkmcnt(0)
	s_setprio 1
	s_barrier
	v_mfma_f32_16x16x32_f16 v[128:131], v[138:141], v[170:173], v[128:131]
	v_mfma_f32_16x16x32_f16 v[124:127], v[146:149], v[170:173], v[124:127]
	v_mfma_f32_16x16x32_f16 v[112:115], v[138:141], v[178:181], v[112:115]
	v_mfma_f32_16x16x32_f16 v[108:111], v[146:149], v[178:181], v[108:111]
	v_mfma_f32_16x16x32_f16 v[96:99], v[138:141], v[198:201], v[96:99]
	v_mfma_f32_16x16x32_f16 v[92:95], v[146:149], v[198:201], v[92:95]
	v_mfma_f32_16x16x32_f16 v[80:83], v[138:141], v[208:211], v[80:83]
	v_mfma_f32_16x16x32_f16 v[76:79], v[146:149], v[208:211], v[76:79]
	v_mfma_f32_16x16x32_f16 v[128:131], v[142:145], v[174:177], v[128:131]
	v_mfma_f32_16x16x32_f16 v[124:127], v[150:153], v[174:177], v[124:127]
	v_mfma_f32_16x16x32_f16 v[112:115], v[142:145], v[190:193], v[112:115]
	v_mfma_f32_16x16x32_f16 v[108:111], v[150:153], v[190:193], v[108:111]
	v_mfma_f32_16x16x32_f16 v[96:99], v[142:145], v[204:207], v[96:99]
	v_mfma_f32_16x16x32_f16 v[92:95], v[150:153], v[204:207], v[92:95]
	v_mfma_f32_16x16x32_f16 v[80:83], v[142:145], v[212:215], v[80:83]
	v_mfma_f32_16x16x32_f16 v[76:79], v[150:153], v[212:215], v[76:79]
	v_mfma_f32_16x16x32_f16 v[120:123], v[154:157], v[170:173], v[120:123]
	v_mfma_f32_16x16x32_f16 v[116:119], v[162:165], v[170:173], v[116:119]
	v_mfma_f32_16x16x32_f16 v[104:107], v[154:157], v[178:181], v[104:107]
	v_mfma_f32_16x16x32_f16 v[100:103], v[162:165], v[178:181], v[100:103]
	v_mfma_f32_16x16x32_f16 v[88:91], v[154:157], v[198:201], v[88:91]
	v_mfma_f32_16x16x32_f16 v[84:87], v[162:165], v[198:201], v[84:87]
	v_mfma_f32_16x16x32_f16 v[72:75], v[154:157], v[208:211], v[72:75]
	v_mfma_f32_16x16x32_f16 v[68:71], v[162:165], v[208:211], v[68:71]
	v_mfma_f32_16x16x32_f16 v[120:123], v[158:161], v[174:177], v[120:123]
	v_mfma_f32_16x16x32_f16 v[116:119], v[166:169], v[174:177], v[116:119]
	v_mfma_f32_16x16x32_f16 v[104:107], v[158:161], v[190:193], v[104:107]
	v_mfma_f32_16x16x32_f16 v[100:103], v[166:169], v[190:193], v[100:103]
	v_mfma_f32_16x16x32_f16 v[88:91], v[158:161], v[204:207], v[88:91]
	v_mfma_f32_16x16x32_f16 v[84:87], v[166:169], v[204:207], v[84:87]
	v_mfma_f32_16x16x32_f16 v[72:75], v[158:161], v[212:215], v[72:75]
	v_mfma_f32_16x16x32_f16 v[68:71], v[166:169], v[212:215], v[68:71]
	s_barrier
	s_setprio 0
	s_add_i32 s65, s86, s49
	s_mov_b32 m0, s65
	s_add_u32 s86, s6, s12
	ds_read_b128 v[170:173], v202 offset:16384
	ds_read_b128 v[174:177], v202 offset:17408
	ds_read_b128 v[178:181], v202 offset:18432
	ds_read_b128 v[190:193], v202 offset:19456
	ds_read_b128 v[198:201], v202 offset:20480
	ds_read_b128 v[204:207], v202 offset:21504
	ds_read_b128 v[208:211], v202 offset:22528
	ds_read_b128 v[212:215], v202 offset:23552
	global_load_lds_dwordx4 v32, s[6:7]
	s_addc_u32 s87, s7, s13
	s_add_i32 m0, s65, 0x2000
	v_lshl_add_u64 v[182:183], s[6:7], 0, v[32:33]
	s_add_u32 s6, s6, s8
	s_addc_u32 s7, s7, s9
	s_add_i32 s8, s45, s49
	global_load_lds_dwordx4 v32, s[86:87]
	s_mov_b32 m0, s8
	v_lshl_add_u64 v[216:217], s[6:7], 0, v[32:33]
	global_load_lds_dwordx4 v32, s[6:7]
	s_add_u32 s6, s6, s12
	s_addc_u32 s7, s7, s13
	s_add_i32 m0, s8, 0x2000
	v_lshl_add_u64 v[234:235], s[6:7], 0, v[32:33]
	global_load_lds_dwordx4 v32, s[6:7]
	s_add_u32 s6, vcc_lo, s12
	v_lshl_add_u64 v[236:237], vcc, 0, v[136:137]
	s_mov_b32 m0, s71
	s_addc_u32 s7, vcc_hi, s13
	global_load_lds_dwordx4 v[236:237], off
	v_lshl_add_u64 v[238:239], s[6:7], 0, v[136:137]
	s_mov_b32 m0, s82
	v_lshl_add_u64 v[194:195], s[86:87], 0, v[32:33]
	global_load_lds_dwordx4 v[238:239], off
	s_waitcnt vmcnt(8)
	s_waitcnt lgkmcnt(0)
	s_setprio 1
	s_barrier
; #define PG8_STAGE(bufoff, gbase, voff, h64) do { \
;         __builtin_amdgcn_global_load_lds((const unsigned*)((const char*)(gbase) + (voff)), (LAS unsigned*)(lds + (bufoff) + ldsw), 16, 0, 0); \
;         __builtin_amdgcn_global_load_lds((const unsigned*)((const char*)(gbase) + (h64) + (voff)), (LAS unsigned*)(lds + (bufoff) + ldsw + 8192), 16, 0, 0); } while (0)
; #define PG8_LDA(dst, b, h) do { _Pragma("unroll") for (int m = 0; m < 4; ++m) { dst[m].lo = *(const LAS f16x8*)(lds + PG8_SA(b, h) + aoff + m * 2048); dst[m].hi = *(const LAS f16x8*)(lds + PG8_SA(b, h) + aoff + m * 2048 + 1024); } } while (0)
; #define PG8_LDB(dst, b, h) do { _Pragma("unroll") for (int n = 0; n < 2; ++n) { dst[n].lo = *(const LAS f16x8*)(lds + PG8_SB(b, h) + boff + n * 2048); dst[n].hi = *(const LAS f16x8*)(lds + PG8_SB(b, h) + boff + n * 2048 + 1024); } } while (0)
; #define PG8_WAIT_V(n) asm volatile("s_waitcnt vmcnt(" #n ")" ::: "memory")
; #define PG8_WAIT_L(n) asm volatile("s_waitcnt lgkmcnt(" #n ")" ::: "memory")
; #define PG8_BAR __builtin_amdgcn_s_barrier()
; #define PG8_SCHED __builtin_amdgcn_sched_barrier(0)
; template <bool F8 = false, class Sched, class Epi>
; __device__ __forceinline__ void gemm_phase(LAS unsigned char* lds, const Sched& S, const Epi& E) {
;     ...
;             PG8_WAIT_V(8); PG8_WAIT_L(0); PG8_BAR; PG8_MMA(1, 0, At, B0); PG8_MMA(1, 1, At, B1); PG8_BAR; PG8_SCHED;
;             PG8_LDB(B0, 1, 0); PG8_LDB(B1, 1, 1); PG8_SCHED; PG8_LDA(At, 1, 0); PG8_STAGE(PG8_SA(0, 1), a2 + hs2, vA2, h2);
;             PG8_WAIT_V(8); PG8_WAIT_L(0); PG8_BAR; PG8_MMA(0, 0, At, B0); PG8_MMA(0, 1, At, B1); PG8_BAR; PG8_SCHED;
	v_mfma_f32_16x16x32_f16 v[64:67], v[138:141], v[170:173], v[64:67]
	v_mfma_f32_16x16x32_f16 v[60:63], v[146:149], v[170:173], v[60:63]
	v_mfma_f32_16x16x32_f16 v[48:51], v[138:141], v[178:181], v[48:51]
	v_mfma_f32_16x16x32_f16 v[44:47], v[146:149], v[178:181], v[44:47]
	v_mfma_f32_16x16x32_f16 v[28:31], v[138:141], v[198:201], v[28:31]
	v_mfma_f32_16x16x32_f16 v[24:27], v[146:149], v[198:201], v[24:27]
	v_mfma_f32_16x16x32_f16 v[12:15], v[138:141], v[208:211], v[12:15]
	v_mfma_f32_16x16x32_f16 v[8:11], v[146:149], v[208:211], v[8:11]
	v_mfma_f32_16x16x32_f16 v[64:67], v[142:145], v[174:177], v[64:67]
	v_mfma_f32_16x16x32_f16 v[60:63], v[150:153], v[174:177], v[60:63]
	v_mfma_f32_16x16x32_f16 v[48:51], v[142:145], v[190:193], v[48:51]
	v_mfma_f32_16x16x32_f16 v[44:47], v[150:153], v[190:193], v[44:47]
	v_mfma_f32_16x16x32_f16 v[28:31], v[142:145], v[204:207], v[28:31]
	v_mfma_f32_16x16x32_f16 v[24:27], v[150:153], v[204:207], v[24:27]
	v_mfma_f32_16x16x32_f16 v[12:15], v[142:145], v[212:215], v[12:15]
	v_mfma_f32_16x16x32_f16 v[8:11], v[150:153], v[212:215], v[8:11]
	v_mfma_f32_16x16x32_f16 v[56:59], v[154:157], v[170:173], v[56:59]
	v_mfma_f32_16x16x32_f16 v[52:55], v[162:165], v[170:173], v[52:55]
	v_mfma_f32_16x16x32_f16 v[40:43], v[154:157], v[178:181], v[40:43]
	v_mfma_f32_16x16x32_f16 v[36:39], v[162:165], v[178:181], v[36:39]
	v_mfma_f32_16x16x32_f16 v[20:23], v[154:157], v[198:201], v[20:23]
	v_mfma_f32_16x16x32_f16 v[16:19], v[162:165], v[198:201], v[16:19]
	v_mfma_f32_16x16x32_f16 v[4:7], v[154:157], v[208:211], v[4:7]
	v_mfma_f32_16x16x32_f16 v[0:3], v[162:165], v[208:211], v[0:3]
	v_mfma_f32_16x16x32_f16 v[56:59], v[158:161], v[174:177], v[56:59]
	v_mfma_f32_16x16x32_f16 v[52:55], v[166:169], v[174:177], v[52:55]
	v_mfma_f32_16x16x32_f16 v[40:43], v[158:161], v[190:193], v[40:43]
	v_mfma_f32_16x16x32_f16 v[36:39], v[166:169], v[190:193], v[36:39]
	v_mfma_f32_16x16x32_f16 v[20:23], v[158:161], v[204:207], v[20:23]
	v_mfma_f32_16x16x32_f16 v[16:19], v[166:169], v[204:207], v[16:19]
	v_mfma_f32_16x16x32_f16 v[4:7], v[158:161], v[212:215], v[4:7]
	v_mfma_f32_16x16x32_f16 v[0:3], v[166:169], v[212:215], v[0:3]
	s_barrier
	s_setprio 0
	s_add_i32 s8, 0, 0x18000
	v_add_u32_e32 v32, s8, v187
	s_add_i32 s9, 0, 0x1c000
	ds_read_b128 v[138:141], v32
	ds_read_b128 v[142:145], v32 offset:1024
	ds_read_b128 v[146:149], v32 offset:2048
	ds_read_b128 v[150:153], v32 offset:3072
	v_add_u32_e32 v32, s9, v187
	ds_read_b128 v[154:157], v32
	ds_read_b128 v[158:161], v32 offset:1024
	ds_read_b128 v[162:165], v32 offset:2048
	ds_read_b128 v[166:169], v32 offset:3072
	s_add_u32 s6, vcc_lo, s84
	s_addc_u32 s7, vcc_hi, s85
	v_lshl_add_u64 v[240:241], s[6:7], 0, v[136:137]
	s_add_u32 s6, s6, s12
	s_mov_b32 m0, s83
	s_addc_u32 s7, s7, s13
	ds_read_b128 v[170:173], v202 offset:32768
	ds_read_b128 v[174:177], v202 offset:33792
	ds_read_b128 v[178:181], v202 offset:34816
	ds_read_b128 v[190:193], v202 offset:35840
	ds_read_b128 v[198:201], v202 offset:36864
	ds_read_b128 v[204:207], v202 offset:37888
	ds_read_b128 v[208:211], v202 offset:38912
	ds_read_b128 v[212:215], v202 offset:39936
	global_load_lds_dwordx4 v[240:241], off
	v_lshl_add_u64 v[136:137], s[6:7], 0, v[136:137]
	s_mov_b32 m0, s44
	s_nop 0
	global_load_lds_dwordx4 v[136:137], off
	s_waitcnt vmcnt(8)
	s_waitcnt lgkmcnt(0)
	s_setprio 1
	s_barrier
	v_mfma_f32_16x16x32_f16 v[128:131], v[138:141], v[170:173], v[128:131]
	v_mfma_f32_16x16x32_f16 v[124:127], v[146:149], v[170:173], v[124:127]
	v_mfma_f32_16x16x32_f16 v[112:115], v[138:141], v[178:181], v[112:115]
	v_mfma_f32_16x16x32_f16 v[108:111], v[146:149], v[178:181], v[108:111]
	v_mfma_f32_16x16x32_f16 v[96:99], v[138:141], v[198:201], v[96:99]
	v_mfma_f32_16x16x32_f16 v[92:95], v[146:149], v[198:201], v[92:95]
	v_mfma_f32_16x16x32_f16 v[80:83], v[138:141], v[208:211], v[80:83]
	v_mfma_f32_16x16x32_f16 v[76:79], v[146:149], v[208:211], v[76:79]
	v_mfma_f32_16x16x32_f16 v[128:131], v[142:145], v[174:177], v[128:131]
	v_mfma_f32_16x16x32_f16 v[124:127], v[150:153], v[174:177], v[124:127]
	v_mfma_f32_16x16x32_f16 v[112:115], v[142:145], v[190:193], v[112:115]
	v_mfma_f32_16x16x32_f16 v[108:111], v[150:153], v[190:193], v[108:111]
	v_mfma_f32_16x16x32_f16 v[96:99], v[142:145], v[204:207], v[96:99]
	v_mfma_f32_16x16x32_f16 v[92:95], v[150:153], v[204:207], v[92:95]
	v_mfma_f32_16x16x32_f16 v[80:83], v[142:145], v[212:215], v[80:83]
	v_mfma_f32_16x16x32_f16 v[76:79], v[150:153], v[212:215], v[76:79]
	v_mfma_f32_16x16x32_f16 v[120:123], v[154:157], v[170:173], v[120:123]
	v_mfma_f32_16x16x32_f16 v[116:119], v[162:165], v[170:173], v[116:119]
	v_mfma_f32_16x16x32_f16 v[104:107], v[154:157], v[178:181], v[104:107]
	v_mfma_f32_16x16x32_f16 v[100:103], v[162:165], v[178:181], v[100:103]
	v_mfma_f32_16x16x32_f16 v[88:91], v[154:157], v[198:201], v[88:91]
	v_mfma_f32_16x16x32_f16 v[84:87], v[162:165], v[198:201], v[84:87]
	v_mfma_f32_16x16x32_f16 v[72:75], v[154:157], v[208:211], v[72:75]
	v_mfma_f32_16x16x32_f16 v[68:71], v[162:165], v[208:211], v[68:71]
	v_mfma_f32_16x16x32_f16 v[120:123], v[158:161], v[174:177], v[120:123]
	v_mfma_f32_16x16x32_f16 v[116:119], v[166:169], v[174:177], v[116:119]
	v_mfma_f32_16x16x32_f16 v[104:107], v[158:161], v[190:193], v[104:107]
	v_mfma_f32_16x16x32_f16 v[100:103], v[166:169], v[190:193], v[100:103]
	v_mfma_f32_16x16x32_f16 v[88:91], v[158:161], v[204:207], v[88:91]
	v_mfma_f32_16x16x32_f16 v[84:87], v[166:169], v[204:207], v[84:87]
	v_mfma_f32_16x16x32_f16 v[72:75], v[158:161], v[212:215], v[72:75]
	v_mfma_f32_16x16x32_f16 v[68:71], v[166:169], v[212:215], v[68:71]
	s_barrier
; #define PG8_STAGE(bufoff, gbase, voff, h64) do { \
;         __builtin_amdgcn_global_load_lds((const unsigned*)((const char*)(gbase) + (voff)), (LAS unsigned*)(lds + (bufoff) + ldsw), 16, 0, 0); \
;         __builtin_amdgcn_global_load_lds((const unsigned*)((const char*)(gbase) + (h64) + (voff)), (LAS unsigned*)(lds + (bufoff) + ldsw + 8192), 16, 0, 0); } while (0)
; #define PG8_LDA(dst, b, h) do { _Pragma("unroll") for (int m = 0; m < 4; ++m) { dst[m].lo = *(const LAS f16x8*)(lds + PG8_SA(b, h) + aoff + m * 2048); dst[m].hi = *(const LAS f16x8*)(lds + PG8_SA(b, h) + aoff + m * 2048 + 1024); } } while (0)
; #define PG8_WAIT_V(n) asm volatile("s_waitcnt vmcnt(" #n ")" ::: "memory")
; #define PG8_WAIT_L(n) asm volatile("s_waitcnt lgkmcnt(" #n ")" ::: "memory")
; #define PG8_BAR __builtin_amdgcn_s_barrier()
; #define PG8_SCHED __builtin_amdgcn_sched_barrier(0)
; template <bool F8 = false, class Sched, class Epi>
; __device__ __forceinline__ void gemm_phase(LAS unsigned char* lds, const Sched& S, const Epi& E) {
;     ...
;             PG8_LDA(At, 1, 1); PG8_STAGE(PG8_SB(1, 0), b3, vB2, h2); PG8_STAGE(PG8_SB(1, 1), b3 + bhs2, vB2, h2); PG8_STAGE(PG8_SA(1, 0), a3, vA2, h2);
;             PG8_WAIT_V(8); PG8_WAIT_L(0); PG8_BAR; PG8_MMA(1, 0, At, B0); PG8_MMA(1, 1, At, B1); PG8_BAR; PG8_SCHED;
	s_setprio 0
	s_add_i32 s6, s8, s49
	v_lshl_add_u64 v[136:137], v[182:183], 0, s[40:41]
	s_mov_b32 m0, s6
	ds_read_b128 v[170:173], v202 offset:49152
	ds_read_b128 v[174:177], v202 offset:50176
	ds_read_b128 v[178:181], v202 offset:51200
	ds_read_b128 v[190:193], v202 offset:52224
	ds_read_b128 v[198:201], v202 offset:53248
	ds_read_b128 v[204:207], v202 offset:54272
	ds_read_b128 v[208:211], v202 offset:55296
	ds_read_b128 v[212:215], v202 offset:56320
	global_load_lds_dwordx4 v[136:137], off
	v_lshl_add_u64 v[136:137], v[194:195], 0, s[40:41]
	s_add_i32 m0, s6, 0x2000
	s_add_i32 s6, s9, s49
	global_load_lds_dwordx4 v[136:137], off
	v_lshl_add_u64 v[136:137], v[216:217], 0, s[40:41]
	s_mov_b32 m0, s6
	s_nop 0
	global_load_lds_dwordx4 v[136:137], off
	v_lshl_add_u64 v[136:137], v[234:235], 0, s[40:41]
	s_add_i32 m0, s6, 0x2000
	s_nop 0
	global_load_lds_dwordx4 v[136:137], off
	v_lshl_add_u64 v[136:137], v[236:237], 0, s[40:41]
	s_mov_b32 m0, s92
	s_nop 0
	global_load_lds_dwordx4 v[136:137], off
	v_lshl_add_u64 v[136:137], v[238:239], 0, s[40:41]
	s_mov_b32 m0, s93
	s_nop 0
	global_load_lds_dwordx4 v[136:137], off
	s_waitcnt vmcnt(8)
	s_waitcnt lgkmcnt(0)
	s_setprio 1
	s_barrier
	v_mfma_f32_16x16x32_f16 v[64:67], v[138:141], v[170:173], v[64:67]
	v_mfma_f32_16x16x32_f16 v[60:63], v[146:149], v[170:173], v[60:63]
	v_mfma_f32_16x16x32_f16 v[48:51], v[138:141], v[178:181], v[48:51]
	v_mfma_f32_16x16x32_f16 v[44:47], v[146:149], v[178:181], v[44:47]
	v_mfma_f32_16x16x32_f16 v[28:31], v[138:141], v[198:201], v[28:31]
	v_mfma_f32_16x16x32_f16 v[24:27], v[146:149], v[198:201], v[24:27]
	v_mfma_f32_16x16x32_f16 v[12:15], v[138:141], v[208:211], v[12:15]
	v_mfma_f32_16x16x32_f16 v[8:11], v[146:149], v[208:211], v[8:11]
	v_mfma_f32_16x16x32_f16 v[64:67], v[142:145], v[174:177], v[64:67]
	v_mfma_f32_16x16x32_f16 v[60:63], v[150:153], v[174:177], v[60:63]
	v_mfma_f32_16x16x32_f16 v[48:51], v[142:145], v[190:193], v[48:51]
	v_mfma_f32_16x16x32_f16 v[44:47], v[150:153], v[190:193], v[44:47]
	v_mfma_f32_16x16x32_f16 v[28:31], v[142:145], v[204:207], v[28:31]
	v_mfma_f32_16x16x32_f16 v[24:27], v[150:153], v[204:207], v[24:27]
	v_mfma_f32_16x16x32_f16 v[12:15], v[142:145], v[212:215], v[12:15]
	v_mfma_f32_16x16x32_f16 v[8:11], v[150:153], v[212:215], v[8:11]
	v_mfma_f32_16x16x32_f16 v[56:59], v[154:157], v[170:173], v[56:59]
	v_mfma_f32_16x16x32_f16 v[52:55], v[162:165], v[170:173], v[52:55]
	v_mfma_f32_16x16x32_f16 v[40:43], v[154:157], v[178:181], v[40:43]
	v_mfma_f32_16x16x32_f16 v[36:39], v[162:165], v[178:181], v[36:39]
	v_mfma_f32_16x16x32_f16 v[20:23], v[154:157], v[198:201], v[20:23]
	v_mfma_f32_16x16x32_f16 v[16:19], v[162:165], v[198:201], v[16:19]
	v_mfma_f32_16x16x32_f16 v[4:7], v[154:157], v[208:211], v[4:7]
	v_mfma_f32_16x16x32_f16 v[0:3], v[162:165], v[208:211], v[0:3]
	v_mfma_f32_16x16x32_f16 v[56:59], v[158:161], v[174:177], v[56:59]
	v_mfma_f32_16x16x32_f16 v[52:55], v[166:169], v[174:177], v[52:55]
	v_mfma_f32_16x16x32_f16 v[40:43], v[158:161], v[190:193], v[40:43]
	v_mfma_f32_16x16x32_f16 v[36:39], v[166:169], v[190:193], v[36:39]
	v_mfma_f32_16x16x32_f16 v[20:23], v[158:161], v[204:207], v[20:23]
	v_mfma_f32_16x16x32_f16 v[16:19], v[166:169], v[204:207], v[16:19]
	v_mfma_f32_16x16x32_f16 v[4:7], v[158:161], v[212:215], v[4:7]
	v_mfma_f32_16x16x32_f16 v[0:3], v[166:169], v[212:215], v[0:3]
	s_barrier
	s_setprio 0
	s_add_u32 s10, s10, 0x100
	s_addc_u32 s11, s11, 0
	s_cmp_ge_u32 s79, s36
	s_cbranch_scc1 .LBB0_217
